# removed the compiler's s_waitcnt vmcnt(0) in front of the EP_RES and EP_SCALET K-loops (only LDS-DMA stages are in flight there; the template's counted waits cover them)
# speedup vs baseline: 1.0019x; 1.0019x over previous
.LBB0_276:
	s_add_u32 s3, s20, 0x100
	s_addc_u32 s34, s21, 0
	s_add_u32 s8, s30, 0x80
	v_mov_b64_e32 v[0:1], 0
	v_mov_b64_e32 v[2:3], 0
	v_mov_b64_e32 v[4:5], 0
	v_mov_b64_e32 v[6:7], 0
	v_mov_b64_e32 v[8:9], 0
	v_mov_b64_e32 v[10:11], 0
	v_mov_b64_e32 v[12:13], 0
	v_mov_b64_e32 v[14:15], 0
	v_mov_b64_e32 v[16:17], 0
	v_mov_b64_e32 v[18:19], 0
	v_mov_b64_e32 v[20:21], 0
	v_mov_b64_e32 v[22:23], 0
	v_mov_b64_e32 v[24:25], 0
	v_mov_b64_e32 v[26:27], 0
	v_mov_b64_e32 v[28:29], 0
	v_mov_b64_e32 v[30:31], 0
	v_mov_b64_e32 v[32:33], 0
	v_mov_b64_e32 v[34:35], 0
	v_mov_b64_e32 v[36:37], 0
	v_mov_b64_e32 v[38:39], 0
	v_mov_b64_e32 v[40:41], 0
	v_mov_b64_e32 v[42:43], 0
	v_mov_b64_e32 v[44:45], 0
	v_mov_b64_e32 v[46:47], 0
	v_mov_b64_e32 v[48:49], 0
	v_mov_b64_e32 v[50:51], 0
	v_mov_b64_e32 v[52:53], 0
	v_mov_b64_e32 v[54:55], 0
	v_mov_b64_e32 v[56:57], 0
	v_mov_b64_e32 v[58:59], 0
	v_mov_b64_e32 v[60:61], 0
	v_mov_b64_e32 v[62:63], 0
	v_mov_b64_e32 v[64:65], 0
	v_mov_b64_e32 v[66:67], 0
	v_mov_b64_e32 v[68:69], 0
	v_mov_b64_e32 v[70:71], 0
	v_mov_b64_e32 v[72:73], 0
	v_mov_b64_e32 v[74:75], 0
	v_mov_b64_e32 v[76:77], 0
	v_mov_b64_e32 v[78:79], 0
	v_mov_b64_e32 v[80:81], 0
	v_mov_b64_e32 v[82:83], 0
	v_mov_b64_e32 v[84:85], 0
	v_mov_b64_e32 v[86:87], 0
	v_mov_b64_e32 v[88:89], 0
	v_mov_b64_e32 v[90:91], 0
	v_mov_b64_e32 v[92:93], 0
	v_mov_b64_e32 v[94:95], 0
	v_mov_b64_e32 v[96:97], 0
	v_mov_b64_e32 v[98:99], 0
	v_mov_b64_e32 v[100:101], 0
	v_mov_b64_e32 v[102:103], 0
	v_mov_b64_e32 v[104:105], 0
	v_mov_b64_e32 v[106:107], 0
	v_mov_b64_e32 v[108:109], 0
	v_mov_b64_e32 v[110:111], 0
	v_mov_b64_e32 v[112:113], 0
	v_mov_b64_e32 v[114:115], 0
	v_mov_b64_e32 v[116:117], 0
	v_mov_b64_e32 v[118:119], 0
	v_mov_b64_e32 v[120:121], 0
	v_mov_b64_e32 v[122:123], 0
	v_mov_b64_e32 v[124:125], 0
	v_mov_b64_e32 v[126:127], 0
	s_addc_u32 s9, s31, 0
	s_mov_b32 s20, 0
	s_nop 0
	s_nop 0
	s_nop 0
	s_nop 0
	s_nop 0
	s_nop 0
	s_nop 0
	s_nop 0
	s_nop 0
	s_nop 0
	s_nop 0
	s_nop 0
	s_nop 0
	s_nop 0
	s_nop 0
	s_nop 0
	s_nop 0
	s_nop 0
	s_nop 0

.LBB0_408:
	s_add_u32 s17, s12, 0x100
	s_addc_u32 s20, s13, 0
	s_add_u32 s8, s14, 0x80
	v_mov_b64_e32 v[0:1], 0
	v_mov_b64_e32 v[2:3], 0
	v_mov_b64_e32 v[4:5], 0
	v_mov_b64_e32 v[6:7], 0
	v_mov_b64_e32 v[8:9], 0
	v_mov_b64_e32 v[10:11], 0
	v_mov_b64_e32 v[12:13], 0
	v_mov_b64_e32 v[14:15], 0
	v_mov_b64_e32 v[16:17], 0
	v_mov_b64_e32 v[18:19], 0
	v_mov_b64_e32 v[20:21], 0
	v_mov_b64_e32 v[22:23], 0
	v_mov_b64_e32 v[24:25], 0
	v_mov_b64_e32 v[26:27], 0
	v_mov_b64_e32 v[28:29], 0
	v_mov_b64_e32 v[30:31], 0
	v_mov_b64_e32 v[32:33], 0
	v_mov_b64_e32 v[34:35], 0
	v_mov_b64_e32 v[36:37], 0
	v_mov_b64_e32 v[38:39], 0
	v_mov_b64_e32 v[40:41], 0
	v_mov_b64_e32 v[42:43], 0
	v_mov_b64_e32 v[44:45], 0
	v_mov_b64_e32 v[46:47], 0
	v_mov_b64_e32 v[48:49], 0
	v_mov_b64_e32 v[50:51], 0
	v_mov_b64_e32 v[52:53], 0
	v_mov_b64_e32 v[54:55], 0
	v_mov_b64_e32 v[56:57], 0
	v_mov_b64_e32 v[58:59], 0
	v_mov_b64_e32 v[60:61], 0
	v_mov_b64_e32 v[62:63], 0
	v_mov_b64_e32 v[64:65], 0
	v_mov_b64_e32 v[66:67], 0
	v_mov_b64_e32 v[68:69], 0
	v_mov_b64_e32 v[70:71], 0
	v_mov_b64_e32 v[72:73], 0
	v_mov_b64_e32 v[74:75], 0
	v_mov_b64_e32 v[76:77], 0
	v_mov_b64_e32 v[78:79], 0
	v_mov_b64_e32 v[80:81], 0
	v_mov_b64_e32 v[82:83], 0
	v_mov_b64_e32 v[84:85], 0
	v_mov_b64_e32 v[86:87], 0
	v_mov_b64_e32 v[88:89], 0
	v_mov_b64_e32 v[90:91], 0
	v_mov_b64_e32 v[92:93], 0
	v_mov_b64_e32 v[94:95], 0
	v_mov_b64_e32 v[96:97], 0
	v_mov_b64_e32 v[98:99], 0
	v_mov_b64_e32 v[100:101], 0
	v_mov_b64_e32 v[102:103], 0
	v_mov_b64_e32 v[104:105], 0
	v_mov_b64_e32 v[106:107], 0
	v_mov_b64_e32 v[108:109], 0
	v_mov_b64_e32 v[110:111], 0
	v_mov_b64_e32 v[112:113], 0
	v_mov_b64_e32 v[114:115], 0
	v_mov_b64_e32 v[116:117], 0
	v_mov_b64_e32 v[118:119], 0
	v_mov_b64_e32 v[120:121], 0
	v_mov_b64_e32 v[122:123], 0
	v_mov_b64_e32 v[124:125], 0
	v_mov_b64_e32 v[126:127], 0
	s_addc_u32 s9, s15, 0
	s_mov_b32 s10, 0
	s_nop 0
